# A/D epilogues: lane-transposed coalesced stores + rstd-table LDS reads hoisted to one round trip
# speedup vs baseline: 1.0173x; 1.0006x over previous
; __device__ __forceinline__ unsigned cvt_pk_bf16(float lo, float hi) { unsigned r; asm volatile("v_cvt_pk_bf16_f32 %0, %1, %2" : "=v"(r) : "v"(lo), "v"(hi)); return r; }
;     __device__ __forceinline__ void operator()(const f32x4 (&acc)[2][2][4][2], const Unit& u, int wr, int wc, int fr, int fq) const {
;         asm volatile("" : "+v"(fr), "+v"(fq));
;         const int rl0 = wr * 64 + fr, col0 = u.pn * BM + wc * 32 + 8 * fq;
; #pragma unroll
;         for (int ai = 0; ai < 2; ++ai)
; #pragma unroll
;             for (int m = 0; m < 4; ++m) { const int rl = rl0 + ai * HALF + m * 16; bf16_t* rowp = O + (size_t)(u.pm * BM + rl) * ldc + col0;
;                 const float s = rst[u.idx * BM + rl];
; #pragma unroll
;                 for (int bj = 0; bj < 2; ++bj) { f32x4 v0 = acc[ai][bj][m][0] * s, v1 = acc[ai][bj][m][1] * s;
;                     if (ACT == 1) {
; #pragma unroll
;                         for (int e = 0; e < 4; ++e) { const float a = fmaxf(v0[e], 0.f), b = fmaxf(v1[e], 0.f); v0[e] = a * a; v1[e] = b * b; } }
;                     u32x4 w; w.x = cvt_pk_bf16(v0[0], v0[1]); w.y = cvt_pk_bf16(v0[2], v0[3]); w.z = cvt_pk_bf16(v1[0], v1[1]); w.w = cvt_pk_bf16(v1[2], v1[3]);
;                     __builtin_nontemporal_store(w, (u32x4*)(rowp + bj * HALF)); } }
;     }
.LBB0_194:
	v_mbcnt_lo_u32_b32 v246, -1, 0
	v_mbcnt_hi_u32_b32 v246, -1, v246
	v_and_b32_e32 v249, 3, v246
	v_lshrrev_b32_e32 v181, 4, v246
	v_sub_u32_e32 v181, v249, v181
	v_lshlrev_b32_e32 v181, 4, v181
	v_and_b32_e32 v180, 15, v246
	v_lshrrev_b32_e32 v246, 2, v246
	v_sub_u32_e32 v180, v246, v180
	v_lshl_add_u32 v180, v180, 12, v181
	v_ashrrev_i32_e32 v181, 31, v180
	v_lshl_add_u32 v246, v249, 4, v246
	v_lshlrev_b32_e32 v246, 2, v246
	s_lshl_b32 s41, s78, 8
	v_mov_b32_e32 v142, v131
	v_mov_b32_e32 v143, v146
	s_or_b32 s41, s41, s68
	s_andn2_b64 vcc, exec, s[44:45]
	v_lshl_add_u32 v144, v143, 3, s41
	s_lshl_b32 s41, s76, 10
	v_add_u32_e32 v149, s65, v142
	s_add_i32 s41, s41, 0
	v_lshl_add_u32 v142, s77, 8, v149
	v_lshl_add_u32 v149, v149, 2, s41
	v_add_u32_e32 v149, 0x20000, v149
	ds_read_b32 v150, v149
	ds_read_b32 v196, v149 offset:64
	ds_read_b32 v197, v149 offset:128
	ds_read_b32 v198, v149 offset:192
	ds_read_b32 v199, v149 offset:512
	ds_read_b32 v200, v149 offset:576
	ds_read_b32 v201, v149 offset:640
	ds_read_b32 v202, v149 offset:704
	v_ashrrev_i32_e32 v143, 31, v142
	v_ashrrev_i32_e32 v145, 31, v144
	v_lshlrev_b64 v[152:153], 12, v[142:143]
	v_lshl_add_u64 v[152:153], s[36:37], 0, v[152:153]
	v_lshlrev_b64 v[144:145], 1, v[144:145]
	v_lshl_add_u64 v[152:153], v[152:153], 0, v[144:145]
	s_waitcnt lgkmcnt(0)
	v_pk_mul_f32 v[128:129], v[128:129], v[150:151] op_sel_hi:[1,0]
	v_pk_mul_f32 v[126:127], v[126:127], v[150:151] op_sel_hi:[1,0]
	v_pk_mul_f32 v[154:155], v[124:125], v[150:151] op_sel_hi:[1,0]
	v_pk_mul_f32 v[124:125], v[122:123], v[150:151] op_sel_hi:[1,0]
	v_cvt_pk_bf16_f32 v122, v126, v127
	v_cvt_pk_bf16_f32 v123, v128, v129
	v_pk_mul_f32 v[120:121], v[120:121], v[150:151] op_sel_hi:[1,0]
	v_cvt_pk_bf16_f32 v124, v124, v125
	v_cvt_pk_bf16_f32 v125, v154, v155
	ds_bpermute_b32 v156, v246, v122
	ds_bpermute_b32 v157, v246, v123
	ds_bpermute_b32 v158, v246, v124
	ds_bpermute_b32 v159, v246, v125
	v_lshl_add_u64 v[164:165], v[152:153], 0, v[180:181]
	v_pk_mul_f32 v[118:119], v[118:119], v[150:151] op_sel_hi:[1,0]
	s_mov_b64 s[44:45], -1
	v_pk_mul_f32 v[122:123], v[116:117], v[150:151] op_sel_hi:[1,0]
	v_pk_mul_f32 v[116:117], v[114:115], v[150:151] op_sel_hi:[1,0]
	v_cvt_pk_bf16_f32 v114, v118, v119
	v_cvt_pk_bf16_f32 v115, v120, v121
	s_nop 0
	v_cvt_pk_bf16_f32 v116, v116, v117
	v_cvt_pk_bf16_f32 v117, v122, v123
	ds_bpermute_b32 v160, v246, v114
	ds_bpermute_b32 v161, v246, v115
	ds_bpermute_b32 v162, v246, v116
	ds_bpermute_b32 v163, v246, v117
	v_lshl_add_u64 v[178:179], v[152:153], 0, v[180:181]
	s_waitcnt lgkmcnt(4)
	global_store_dwordx4 v[164:165], v[156:159], off nt
	s_waitcnt lgkmcnt(4)
	v_mov_b32_e32 v116, v196
	v_pk_mul_f32 v[112:113], v[112:113], v[116:117] op_sel_hi:[1,0]
	v_add_u32_e32 v114, 16, v142
	v_ashrrev_i32_e32 v115, 31, v114
	v_lshlrev_b64 v[114:115], 12, v[114:115]
	v_lshl_add_u64 v[114:115], s[36:37], 0, v[114:115]
	v_lshl_add_u64 v[114:115], v[114:115], 0, v[144:145]
	v_pk_mul_f32 v[110:111], v[110:111], v[116:117] op_sel_hi:[1,0]
	v_pk_mul_f32 v[118:119], v[108:109], v[116:117] op_sel_hi:[1,0]
	v_pk_mul_f32 v[108:109], v[106:107], v[116:117] op_sel_hi:[1,0]
	v_cvt_pk_bf16_f32 v106, v110, v111
	v_cvt_pk_bf16_f32 v107, v112, v113
	v_pk_mul_f32 v[104:105], v[104:105], v[116:117] op_sel_hi:[1,0]
	v_cvt_pk_bf16_f32 v108, v108, v109
	v_cvt_pk_bf16_f32 v109, v118, v119
	ds_bpermute_b32 v156, v246, v106
	ds_bpermute_b32 v157, v246, v107
	ds_bpermute_b32 v158, v246, v108
	ds_bpermute_b32 v159, v246, v109
	v_lshl_add_u64 v[164:165], v[114:115], 0, v[180:181]
	s_waitcnt lgkmcnt(4)
	global_store_dwordx4 v[178:179], v[160:163], off offset:256 nt
	v_pk_mul_f32 v[102:103], v[102:103], v[116:117] op_sel_hi:[1,0]
	s_nop 0
	v_pk_mul_f32 v[106:107], v[100:101], v[116:117] op_sel_hi:[1,0]
	v_pk_mul_f32 v[100:101], v[98:99], v[116:117] op_sel_hi:[1,0]
	v_cvt_pk_bf16_f32 v98, v102, v103
	v_cvt_pk_bf16_f32 v99, v104, v105
	s_nop 0
	v_cvt_pk_bf16_f32 v100, v100, v101
	v_cvt_pk_bf16_f32 v101, v106, v107
	ds_bpermute_b32 v160, v246, v98
	ds_bpermute_b32 v161, v246, v99
	ds_bpermute_b32 v162, v246, v100
	ds_bpermute_b32 v163, v246, v101
	v_lshl_add_u64 v[178:179], v[114:115], 0, v[180:181]
	s_waitcnt lgkmcnt(4)
	global_store_dwordx4 v[164:165], v[156:159], off nt
	s_waitcnt lgkmcnt(4)
	v_mov_b32_e32 v100, v197
	v_pk_mul_f32 v[96:97], v[96:97], v[100:101] op_sel_hi:[1,0]
	v_add_u32_e32 v98, 32, v142
	v_ashrrev_i32_e32 v99, 31, v98
	v_lshlrev_b64 v[98:99], 12, v[98:99]
	v_lshl_add_u64 v[98:99], s[36:37], 0, v[98:99]
	v_lshl_add_u64 v[98:99], v[98:99], 0, v[144:145]
	v_pk_mul_f32 v[94:95], v[94:95], v[100:101] op_sel_hi:[1,0]
	v_pk_mul_f32 v[102:103], v[92:93], v[100:101] op_sel_hi:[1,0]
	v_pk_mul_f32 v[92:93], v[90:91], v[100:101] op_sel_hi:[1,0]
	v_cvt_pk_bf16_f32 v90, v94, v95
	v_cvt_pk_bf16_f32 v91, v96, v97
	v_pk_mul_f32 v[88:89], v[88:89], v[100:101] op_sel_hi:[1,0]
	v_cvt_pk_bf16_f32 v92, v92, v93
	v_cvt_pk_bf16_f32 v93, v102, v103
	ds_bpermute_b32 v156, v246, v90
	ds_bpermute_b32 v157, v246, v91
	ds_bpermute_b32 v158, v246, v92
	ds_bpermute_b32 v159, v246, v93
	v_lshl_add_u64 v[164:165], v[98:99], 0, v[180:181]
	s_waitcnt lgkmcnt(4)
	global_store_dwordx4 v[178:179], v[160:163], off offset:256 nt
	v_pk_mul_f32 v[86:87], v[86:87], v[100:101] op_sel_hi:[1,0]
	s_nop 0
	v_pk_mul_f32 v[90:91], v[84:85], v[100:101] op_sel_hi:[1,0]
	v_pk_mul_f32 v[84:85], v[82:83], v[100:101] op_sel_hi:[1,0]
	v_cvt_pk_bf16_f32 v82, v86, v87
	v_cvt_pk_bf16_f32 v83, v88, v89
	s_nop 0
	v_cvt_pk_bf16_f32 v84, v84, v85
	v_cvt_pk_bf16_f32 v85, v90, v91
	ds_bpermute_b32 v160, v246, v82
	ds_bpermute_b32 v161, v246, v83
	ds_bpermute_b32 v162, v246, v84
	ds_bpermute_b32 v163, v246, v85
	v_lshl_add_u64 v[178:179], v[98:99], 0, v[180:181]
	s_waitcnt lgkmcnt(4)
; __device__ __forceinline__ unsigned cvt_pk_bf16(float lo, float hi) { unsigned r; asm volatile("v_cvt_pk_bf16_f32 %0, %1, %2" : "=v"(r) : "v"(lo), "v"(hi)); return r; }
;     __device__ __forceinline__ void operator()(const f32x4 (&acc)[2][2][4][2], const Unit& u, int wr, int wc, int fr, int fq) const {
;         asm volatile("" : "+v"(fr), "+v"(fq));
;         const int rl0 = wr * 64 + fr, col0 = u.pn * BM + wc * 32 + 8 * fq;
; #pragma unroll
;         for (int ai = 0; ai < 2; ++ai)
; #pragma unroll
;             for (int m = 0; m < 4; ++m) { const int rl = rl0 + ai * HALF + m * 16; bf16_t* rowp = O + (size_t)(u.pm * BM + rl) * ldc + col0;
;                 const float s = rst[u.idx * BM + rl];
; #pragma unroll
;                 for (int bj = 0; bj < 2; ++bj) { f32x4 v0 = acc[ai][bj][m][0] * s, v1 = acc[ai][bj][m][1] * s;
;                     if (ACT == 1) {
; #pragma unroll
;                         for (int e = 0; e < 4; ++e) { const float a = fmaxf(v0[e], 0.f), b = fmaxf(v1[e], 0.f); v0[e] = a * a; v1[e] = b * b; } }
;                     u32x4 w; w.x = cvt_pk_bf16(v0[0], v0[1]); w.y = cvt_pk_bf16(v0[2], v0[3]); w.z = cvt_pk_bf16(v1[0], v1[1]); w.w = cvt_pk_bf16(v1[2], v1[3]);
;                     __builtin_nontemporal_store(w, (u32x4*)(rowp + bj * HALF)); } }
;     }
	global_store_dwordx4 v[164:165], v[156:159], off nt
	s_waitcnt lgkmcnt(4)
	v_mov_b32_e32 v84, v198
	v_pk_mul_f32 v[80:81], v[80:81], v[84:85] op_sel_hi:[1,0]
	v_add_u32_e32 v82, 48, v142
	v_ashrrev_i32_e32 v83, 31, v82
	v_lshlrev_b64 v[82:83], 12, v[82:83]
	v_lshl_add_u64 v[82:83], s[36:37], 0, v[82:83]
	v_lshl_add_u64 v[82:83], v[82:83], 0, v[144:145]
	v_pk_mul_f32 v[78:79], v[78:79], v[84:85] op_sel_hi:[1,0]
	v_pk_mul_f32 v[86:87], v[76:77], v[84:85] op_sel_hi:[1,0]
	v_pk_mul_f32 v[76:77], v[74:75], v[84:85] op_sel_hi:[1,0]
	v_cvt_pk_bf16_f32 v74, v78, v79
	v_cvt_pk_bf16_f32 v75, v80, v81
	v_pk_mul_f32 v[72:73], v[72:73], v[84:85] op_sel_hi:[1,0]
	v_cvt_pk_bf16_f32 v76, v76, v77
	v_cvt_pk_bf16_f32 v77, v86, v87
	ds_bpermute_b32 v156, v246, v74
	ds_bpermute_b32 v157, v246, v75
	ds_bpermute_b32 v158, v246, v76
	ds_bpermute_b32 v159, v246, v77
	v_lshl_add_u64 v[164:165], v[82:83], 0, v[180:181]
	s_waitcnt lgkmcnt(4)
	global_store_dwordx4 v[178:179], v[160:163], off offset:256 nt
	v_pk_mul_f32 v[70:71], v[70:71], v[84:85] op_sel_hi:[1,0]
	s_nop 0
	v_pk_mul_f32 v[74:75], v[68:69], v[84:85] op_sel_hi:[1,0]
	v_pk_mul_f32 v[68:69], v[66:67], v[84:85] op_sel_hi:[1,0]
	v_cvt_pk_bf16_f32 v66, v70, v71
	v_cvt_pk_bf16_f32 v67, v72, v73
	s_nop 0
	v_cvt_pk_bf16_f32 v68, v68, v69
	v_cvt_pk_bf16_f32 v69, v74, v75
	ds_bpermute_b32 v160, v246, v66
	ds_bpermute_b32 v161, v246, v67
	ds_bpermute_b32 v162, v246, v68
	ds_bpermute_b32 v163, v246, v69
	v_lshl_add_u64 v[178:179], v[82:83], 0, v[180:181]
	s_waitcnt lgkmcnt(4)
	global_store_dwordx4 v[164:165], v[156:159], off nt
	s_waitcnt lgkmcnt(4)
	v_mov_b32_e32 v68, v199
	v_pk_mul_f32 v[64:65], v[64:65], v[68:69] op_sel_hi:[1,0]
	v_add_u32_e32 v66, 0x80, v142
	v_ashrrev_i32_e32 v67, 31, v66
	v_lshlrev_b64 v[66:67], 12, v[66:67]
	v_lshl_add_u64 v[66:67], s[36:37], 0, v[66:67]
	v_lshl_add_u64 v[66:67], v[66:67], 0, v[144:145]
	v_pk_mul_f32 v[62:63], v[62:63], v[68:69] op_sel_hi:[1,0]
	v_pk_mul_f32 v[70:71], v[60:61], v[68:69] op_sel_hi:[1,0]
	v_pk_mul_f32 v[60:61], v[58:59], v[68:69] op_sel_hi:[1,0]
	v_cvt_pk_bf16_f32 v58, v62, v63
	v_cvt_pk_bf16_f32 v59, v64, v65
	v_pk_mul_f32 v[56:57], v[56:57], v[68:69] op_sel_hi:[1,0]
	v_cvt_pk_bf16_f32 v60, v60, v61
	v_cvt_pk_bf16_f32 v61, v70, v71
	ds_bpermute_b32 v156, v246, v58
	ds_bpermute_b32 v157, v246, v59
	ds_bpermute_b32 v158, v246, v60
	ds_bpermute_b32 v159, v246, v61
	v_lshl_add_u64 v[164:165], v[66:67], 0, v[180:181]
	s_waitcnt lgkmcnt(4)
	global_store_dwordx4 v[178:179], v[160:163], off offset:256 nt
	v_pk_mul_f32 v[54:55], v[54:55], v[68:69] op_sel_hi:[1,0]
	s_nop 0
	v_pk_mul_f32 v[58:59], v[52:53], v[68:69] op_sel_hi:[1,0]
	v_pk_mul_f32 v[52:53], v[50:51], v[68:69] op_sel_hi:[1,0]
	v_cvt_pk_bf16_f32 v50, v54, v55
	v_cvt_pk_bf16_f32 v51, v56, v57
	s_nop 0
	v_cvt_pk_bf16_f32 v52, v52, v53
	v_cvt_pk_bf16_f32 v53, v58, v59
	ds_bpermute_b32 v160, v246, v50
	ds_bpermute_b32 v161, v246, v51
	ds_bpermute_b32 v162, v246, v52
	ds_bpermute_b32 v163, v246, v53
	v_lshl_add_u64 v[178:179], v[66:67], 0, v[180:181]
	s_waitcnt lgkmcnt(4)
	global_store_dwordx4 v[164:165], v[156:159], off nt
	s_waitcnt lgkmcnt(4)
	v_mov_b32_e32 v52, v200
	v_pk_mul_f32 v[48:49], v[48:49], v[52:53] op_sel_hi:[1,0]
	v_add_u32_e32 v50, 0x90, v142
	v_ashrrev_i32_e32 v51, 31, v50
	v_lshlrev_b64 v[50:51], 12, v[50:51]
	v_lshl_add_u64 v[50:51], s[36:37], 0, v[50:51]
	v_lshl_add_u64 v[50:51], v[50:51], 0, v[144:145]
	v_pk_mul_f32 v[46:47], v[46:47], v[52:53] op_sel_hi:[1,0]
	v_pk_mul_f32 v[54:55], v[44:45], v[52:53] op_sel_hi:[1,0]
	v_pk_mul_f32 v[44:45], v[42:43], v[52:53] op_sel_hi:[1,0]
	v_cvt_pk_bf16_f32 v42, v46, v47
	v_cvt_pk_bf16_f32 v43, v48, v49
	v_pk_mul_f32 v[40:41], v[40:41], v[52:53] op_sel_hi:[1,0]
	v_cvt_pk_bf16_f32 v44, v44, v45
	v_cvt_pk_bf16_f32 v45, v54, v55
	ds_bpermute_b32 v156, v246, v42
	ds_bpermute_b32 v157, v246, v43
	ds_bpermute_b32 v158, v246, v44
	ds_bpermute_b32 v159, v246, v45
	v_lshl_add_u64 v[164:165], v[50:51], 0, v[180:181]
	s_waitcnt lgkmcnt(4)
; __device__ __forceinline__ unsigned cvt_pk_bf16(float lo, float hi) { unsigned r; asm volatile("v_cvt_pk_bf16_f32 %0, %1, %2" : "=v"(r) : "v"(lo), "v"(hi)); return r; }
;     __device__ __forceinline__ void operator()(const f32x4 (&acc)[2][2][4][2], const Unit& u, int wr, int wc, int fr, int fq) const {
;         asm volatile("" : "+v"(fr), "+v"(fq));
;         const int rl0 = wr * 64 + fr, col0 = u.pn * BM + wc * 32 + 8 * fq;
; #pragma unroll
;         for (int ai = 0; ai < 2; ++ai)
; #pragma unroll
;             for (int m = 0; m < 4; ++m) { const int rl = rl0 + ai * HALF + m * 16; bf16_t* rowp = O + (size_t)(u.pm * BM + rl) * ldc + col0;
;                 const float s = rst[u.idx * BM + rl];
; #pragma unroll
;                 for (int bj = 0; bj < 2; ++bj) { f32x4 v0 = acc[ai][bj][m][0] * s, v1 = acc[ai][bj][m][1] * s;
;                     if (ACT == 1) {
; #pragma unroll
;                         for (int e = 0; e < 4; ++e) { const float a = fmaxf(v0[e], 0.f), b = fmaxf(v1[e], 0.f); v0[e] = a * a; v1[e] = b * b; } }
;                     u32x4 w; w.x = cvt_pk_bf16(v0[0], v0[1]); w.y = cvt_pk_bf16(v0[2], v0[3]); w.z = cvt_pk_bf16(v1[0], v1[1]); w.w = cvt_pk_bf16(v1[2], v1[3]);
;                     __builtin_nontemporal_store(w, (u32x4*)(rowp + bj * HALF)); } }
;     }
	global_store_dwordx4 v[178:179], v[160:163], off offset:256 nt
	v_pk_mul_f32 v[38:39], v[38:39], v[52:53] op_sel_hi:[1,0]
	s_nop 0
	v_pk_mul_f32 v[42:43], v[36:37], v[52:53] op_sel_hi:[1,0]
	v_pk_mul_f32 v[36:37], v[34:35], v[52:53] op_sel_hi:[1,0]
	v_cvt_pk_bf16_f32 v34, v38, v39
	v_cvt_pk_bf16_f32 v35, v40, v41
	s_nop 0
	v_cvt_pk_bf16_f32 v36, v36, v37
	v_cvt_pk_bf16_f32 v37, v42, v43
	ds_bpermute_b32 v160, v246, v34
	ds_bpermute_b32 v161, v246, v35
	ds_bpermute_b32 v162, v246, v36
	ds_bpermute_b32 v163, v246, v37
	v_lshl_add_u64 v[178:179], v[50:51], 0, v[180:181]
	s_waitcnt lgkmcnt(4)
	global_store_dwordx4 v[164:165], v[156:159], off nt
	s_waitcnt lgkmcnt(4)
	v_mov_b32_e32 v36, v201
	v_pk_mul_f32 v[32:33], v[32:33], v[36:37] op_sel_hi:[1,0]
	v_add_u32_e32 v34, 0xa0, v142
	v_ashrrev_i32_e32 v35, 31, v34
	v_lshlrev_b64 v[34:35], 12, v[34:35]
	v_lshl_add_u64 v[34:35], s[36:37], 0, v[34:35]
	v_lshl_add_u64 v[34:35], v[34:35], 0, v[144:145]
	v_pk_mul_f32 v[30:31], v[30:31], v[36:37] op_sel_hi:[1,0]
	v_pk_mul_f32 v[38:39], v[28:29], v[36:37] op_sel_hi:[1,0]
	v_pk_mul_f32 v[28:29], v[26:27], v[36:37] op_sel_hi:[1,0]
	v_cvt_pk_bf16_f32 v26, v30, v31
	v_cvt_pk_bf16_f32 v27, v32, v33
	v_pk_mul_f32 v[24:25], v[24:25], v[36:37] op_sel_hi:[1,0]
	v_cvt_pk_bf16_f32 v28, v28, v29
	v_cvt_pk_bf16_f32 v29, v38, v39
	ds_bpermute_b32 v156, v246, v26
	ds_bpermute_b32 v157, v246, v27
	ds_bpermute_b32 v158, v246, v28
	ds_bpermute_b32 v159, v246, v29
	v_lshl_add_u64 v[164:165], v[34:35], 0, v[180:181]
	s_waitcnt lgkmcnt(4)
	global_store_dwordx4 v[178:179], v[160:163], off offset:256 nt
	v_pk_mul_f32 v[22:23], v[22:23], v[36:37] op_sel_hi:[1,0]
	s_nop 0
	v_pk_mul_f32 v[26:27], v[20:21], v[36:37] op_sel_hi:[1,0]
	v_pk_mul_f32 v[20:21], v[18:19], v[36:37] op_sel_hi:[1,0]
	v_cvt_pk_bf16_f32 v18, v22, v23
	v_cvt_pk_bf16_f32 v19, v24, v25
	s_nop 0
	v_cvt_pk_bf16_f32 v20, v20, v21
	v_cvt_pk_bf16_f32 v21, v26, v27
	ds_bpermute_b32 v160, v246, v18
	ds_bpermute_b32 v161, v246, v19
	ds_bpermute_b32 v162, v246, v20
	ds_bpermute_b32 v163, v246, v21
	v_lshl_add_u64 v[178:179], v[34:35], 0, v[180:181]
	s_waitcnt lgkmcnt(4)
	global_store_dwordx4 v[164:165], v[156:159], off nt
	s_waitcnt lgkmcnt(4)
	v_mov_b32_e32 v20, v202
	v_pk_mul_f32 v[16:17], v[16:17], v[20:21] op_sel_hi:[1,0]
	v_add_u32_e32 v18, 0xb0, v142
	v_ashrrev_i32_e32 v19, 31, v18
	v_lshlrev_b64 v[18:19], 12, v[18:19]
	v_lshl_add_u64 v[18:19], s[36:37], 0, v[18:19]
	v_lshl_add_u64 v[18:19], v[18:19], 0, v[144:145]
	v_pk_mul_f32 v[14:15], v[14:15], v[20:21] op_sel_hi:[1,0]
	v_pk_mul_f32 v[22:23], v[12:13], v[20:21] op_sel_hi:[1,0]
	v_pk_mul_f32 v[12:13], v[10:11], v[20:21] op_sel_hi:[1,0]
	v_cvt_pk_bf16_f32 v10, v14, v15
	v_cvt_pk_bf16_f32 v11, v16, v17
	v_pk_mul_f32 v[8:9], v[8:9], v[20:21] op_sel_hi:[1,0]
	v_cvt_pk_bf16_f32 v12, v12, v13
	v_cvt_pk_bf16_f32 v13, v22, v23
	ds_bpermute_b32 v156, v246, v10
	ds_bpermute_b32 v157, v246, v11
	ds_bpermute_b32 v158, v246, v12
	ds_bpermute_b32 v159, v246, v13
	v_lshl_add_u64 v[164:165], v[18:19], 0, v[180:181]
	s_waitcnt lgkmcnt(4)
	global_store_dwordx4 v[178:179], v[160:163], off offset:256 nt
	v_pk_mul_f32 v[6:7], v[6:7], v[20:21] op_sel_hi:[1,0]
	s_nop 0
	v_pk_mul_f32 v[10:11], v[4:5], v[20:21] op_sel_hi:[1,0]
	v_pk_mul_f32 v[4:5], v[2:3], v[20:21] op_sel_hi:[1,0]
	v_cvt_pk_bf16_f32 v2, v6, v7
	v_cvt_pk_bf16_f32 v3, v8, v9
	s_nop 0
	v_cvt_pk_bf16_f32 v4, v4, v5
	v_cvt_pk_bf16_f32 v5, v10, v11
	ds_bpermute_b32 v160, v246, v2
	ds_bpermute_b32 v161, v246, v3
	ds_bpermute_b32 v162, v246, v4
	ds_bpermute_b32 v163, v246, v5
	v_lshl_add_u64 v[178:179], v[18:19], 0, v[180:181]
	s_waitcnt lgkmcnt(4)
	global_store_dwordx4 v[164:165], v[156:159], off nt
	s_waitcnt lgkmcnt(0)
	global_store_dwordx4 v[178:179], v[160:163], off offset:256 nt
	s_cbranch_vccnz .LBB0_183
	s_andn2_b64 vcc, exec, s[28:29]
	s_cbranch_vccnz .LBB0_182
	s_barrier
	s_branch .LBB0_182

; __device__ __forceinline__ unsigned cvt_pk_bf16(float lo, float hi) { unsigned r; asm volatile("v_cvt_pk_bf16_f32 %0, %1, %2" : "=v"(r) : "v"(lo), "v"(hi)); return r; }
;     __device__ __forceinline__ void operator()(const f32x4 (&acc)[2][2][4][2], const Unit& u, int wr, int wc, int fr, int fq) const {
;         asm volatile("" : "+v"(fr), "+v"(fq));
;         const int rl0 = wr * 64 + fr, col0 = u.pn * BM + wc * 32 + 8 * fq;
; #pragma unroll
;         for (int ai = 0; ai < 2; ++ai)
; #pragma unroll
;             for (int m = 0; m < 4; ++m) { const int rl = rl0 + ai * HALF + m * 16; bf16_t* rowp = O + (size_t)(u.pm * BM + rl) * ldc + col0;
;                 const float s = rst[u.idx * BM + rl];
; #pragma unroll
;                 for (int bj = 0; bj < 2; ++bj) { f32x4 v0 = acc[ai][bj][m][0] * s, v1 = acc[ai][bj][m][1] * s;
;                     if (ACT == 1) {
; #pragma unroll
;                         for (int e = 0; e < 4; ++e) { const float a = fmaxf(v0[e], 0.f), b = fmaxf(v1[e], 0.f); v0[e] = a * a; v1[e] = b * b; } }
;                     u32x4 w; w.x = cvt_pk_bf16(v0[0], v0[1]); w.y = cvt_pk_bf16(v0[2], v0[3]); w.z = cvt_pk_bf16(v1[0], v1[1]); w.w = cvt_pk_bf16(v1[2], v1[3]);
;                     __builtin_nontemporal_store(w, (u32x4*)(rowp + bj * HALF)); } }
;     }
.LBB0_495:
	v_mbcnt_lo_u32_b32 v246, -1, 0
	v_mbcnt_hi_u32_b32 v246, -1, v246
	v_and_b32_e32 v249, 3, v246
	v_lshrrev_b32_e32 v181, 4, v246
	v_sub_u32_e32 v181, v249, v181
	v_lshlrev_b32_e32 v181, 4, v181
	v_and_b32_e32 v180, 15, v246
	v_lshrrev_b32_e32 v246, 2, v246
	v_sub_u32_e32 v180, v246, v180
	v_lshl_add_u32 v180, v180, 13, v181
	v_ashrrev_i32_e32 v181, 31, v180
	v_lshl_add_u32 v246, v249, 4, v246
	v_lshlrev_b32_e32 v246, 2, v246
	s_lshl_b32 s43, s77, 8
	v_mov_b32_e32 v140, v144
	v_mov_b32_e32 v141, v145
	s_or_b32 s43, s43, s64
	s_andn2_b64 vcc, exec, s[46:47]
	v_lshl_add_u32 v142, v141, 3, s43
	s_lshl_b32 s43, s75, 10
	v_add_u32_e32 v148, s63, v140
	s_add_i32 s43, s43, 0
	v_lshl_add_u32 v140, s76, 8, v148
	v_lshl_add_u32 v148, v148, 2, s43
	v_add_u32_e32 v148, 0x20000, v148
	ds_read_b32 v150, v148
	ds_read_b32 v196, v148 offset:64
	ds_read_b32 v197, v148 offset:128
	ds_read_b32 v198, v148 offset:192
	ds_read_b32 v199, v148 offset:512
	ds_read_b32 v200, v148 offset:576
	ds_read_b32 v201, v148 offset:640
	ds_read_b32 v202, v148 offset:704
	v_ashrrev_i32_e32 v141, 31, v140
	v_ashrrev_i32_e32 v143, 31, v142
	v_lshlrev_b64 v[152:153], 13, v[140:141]
	v_lshl_add_u64 v[152:153], s[28:29], 0, v[152:153]
	s_waitcnt lgkmcnt(0)
	v_pk_mul_f32 v[122:123], v[122:123], v[150:151] op_sel_hi:[1,0]
	v_pk_mul_f32 v[126:127], v[126:127], v[150:151] op_sel_hi:[1,0]
	v_pk_mul_f32 v[124:125], v[124:125], v[150:151] op_sel_hi:[1,0]
	v_max_f32_e32 v122, 0, v122
	v_pk_mul_f32 v[128:129], v[128:129], v[150:151] op_sel_hi:[1,0]
	v_mul_f32_e32 v141, v122, v122
	v_max_f32_e32 v122, 0, v127
	v_max_f32_e32 v123, 0, v123
	v_max_f32_e32 v124, 0, v124
	v_lshlrev_b64 v[142:143], 1, v[142:143]
	v_max_f32_e32 v126, 0, v126
	v_mul_f32_e32 v122, v122, v122
	v_mul_f32_e32 v127, v123, v123
	v_max_f32_e32 v123, 0, v128
	v_mul_f32_e32 v128, v124, v124
	v_max_f32_e32 v124, 0, v129
	v_max_f32_e32 v125, 0, v125
	v_pk_mul_f32 v[116:117], v[116:117], v[150:151] op_sel_hi:[1,0]
	v_pk_mul_f32 v[114:115], v[114:115], v[150:151] op_sel_hi:[1,0]
	v_lshl_add_u64 v[152:153], v[152:153], 0, v[142:143]
	v_mul_f32_e32 v126, v126, v126
	v_mul_f32_e32 v123, v123, v123
	v_mul_f32_e32 v124, v124, v124
	v_mul_f32_e32 v125, v125, v125
	v_cvt_pk_bf16_f32 v122, v126, v122
	v_pk_mul_f32 v[120:121], v[120:121], v[150:151] op_sel_hi:[1,0]
	v_pk_mul_f32 v[118:119], v[118:119], v[150:151] op_sel_hi:[1,0]
	v_max_f32_e32 v114, 0, v114
	v_max_f32_e32 v115, 0, v115
	v_max_f32_e32 v116, 0, v116
	v_cvt_pk_bf16_f32 v123, v123, v124
	v_cvt_pk_bf16_f32 v124, v141, v127
	v_cvt_pk_bf16_f32 v125, v128, v125
	ds_bpermute_b32 v156, v246, v122
	ds_bpermute_b32 v157, v246, v123
	ds_bpermute_b32 v158, v246, v124
	ds_bpermute_b32 v159, v246, v125
	v_lshl_add_u64 v[164:165], v[152:153], 0, v[180:181]
	v_max_f32_e32 v118, 0, v118
	v_max_f32_e32 v117, 0, v117
	v_mul_f32_e32 v122, v114, v114
	v_max_f32_e32 v114, 0, v119
	v_mul_f32_e32 v119, v115, v115
	v_max_f32_e32 v115, 0, v120
	v_mul_f32_e32 v120, v116, v116
	v_max_f32_e32 v116, 0, v121
	v_mul_f32_e32 v114, v114, v114
	v_mul_f32_e32 v115, v115, v115
	v_mul_f32_e32 v116, v116, v116
	v_mul_f32_e32 v118, v118, v118
	v_mul_f32_e32 v117, v117, v117
	v_cvt_pk_bf16_f32 v114, v118, v114
	v_cvt_pk_bf16_f32 v115, v115, v116
	v_cvt_pk_bf16_f32 v116, v122, v119
	v_cvt_pk_bf16_f32 v117, v120, v117
	ds_bpermute_b32 v160, v246, v114
	ds_bpermute_b32 v161, v246, v115
	ds_bpermute_b32 v162, v246, v116
	ds_bpermute_b32 v163, v246, v117
	v_lshl_add_u64 v[178:179], v[152:153], 0, v[180:181]
	s_waitcnt lgkmcnt(4)
	global_store_dwordx4 v[164:165], v[156:159], off nt
	s_mov_b64 s[46:47], -1
	v_add_u32_e32 v114, 16, v140
	v_ashrrev_i32_e32 v115, 31, v114
	v_lshlrev_b64 v[114:115], 13, v[114:115]
	s_waitcnt lgkmcnt(4)
	v_mov_b32_e32 v116, v196
	v_pk_mul_f32 v[106:107], v[106:107], v[116:117] op_sel_hi:[1,0]
	v_pk_mul_f32 v[110:111], v[110:111], v[116:117] op_sel_hi:[1,0]
	v_pk_mul_f32 v[108:109], v[108:109], v[116:117] op_sel_hi:[1,0]
	v_max_f32_e32 v106, 0, v106
	v_pk_mul_f32 v[112:113], v[112:113], v[116:117] op_sel_hi:[1,0]
	v_mul_f32_e32 v117, v106, v106
	v_max_f32_e32 v106, 0, v111
	v_max_f32_e32 v107, 0, v107
	v_max_f32_e32 v108, 0, v108
	v_lshl_add_u64 v[114:115], s[28:29], 0, v[114:115]
	v_max_f32_e32 v110, 0, v110
	v_mul_f32_e32 v106, v106, v106
	v_mul_f32_e32 v111, v107, v107
	v_max_f32_e32 v107, 0, v112
	v_mul_f32_e32 v112, v108, v108
	v_max_f32_e32 v108, 0, v113
	v_max_f32_e32 v109, 0, v109
	v_pk_mul_f32 v[100:101], v[100:101], v[116:117] op_sel_hi:[1,0]
	v_pk_mul_f32 v[98:99], v[98:99], v[116:117] op_sel_hi:[1,0]
	v_lshl_add_u64 v[114:115], v[114:115], 0, v[142:143]
	v_mul_f32_e32 v110, v110, v110
	v_mul_f32_e32 v107, v107, v107
	v_mul_f32_e32 v108, v108, v108
	v_mul_f32_e32 v109, v109, v109
	v_cvt_pk_bf16_f32 v106, v110, v106
	v_pk_mul_f32 v[104:105], v[104:105], v[116:117] op_sel_hi:[1,0]
	v_pk_mul_f32 v[102:103], v[102:103], v[116:117] op_sel_hi:[1,0]
	v_max_f32_e32 v98, 0, v98
	v_max_f32_e32 v99, 0, v99
	v_max_f32_e32 v100, 0, v100
	v_cvt_pk_bf16_f32 v107, v107, v108
	v_cvt_pk_bf16_f32 v108, v117, v111
	v_cvt_pk_bf16_f32 v109, v112, v109
	ds_bpermute_b32 v156, v246, v106
	ds_bpermute_b32 v157, v246, v107
	ds_bpermute_b32 v158, v246, v108
	ds_bpermute_b32 v159, v246, v109
	v_lshl_add_u64 v[164:165], v[114:115], 0, v[180:181]
	s_waitcnt lgkmcnt(4)
; __device__ __forceinline__ unsigned cvt_pk_bf16(float lo, float hi) { unsigned r; asm volatile("v_cvt_pk_bf16_f32 %0, %1, %2" : "=v"(r) : "v"(lo), "v"(hi)); return r; }
;     __device__ __forceinline__ void operator()(const f32x4 (&acc)[2][2][4][2], const Unit& u, int wr, int wc, int fr, int fq) const {
;         asm volatile("" : "+v"(fr), "+v"(fq));
;         const int rl0 = wr * 64 + fr, col0 = u.pn * BM + wc * 32 + 8 * fq;
; #pragma unroll
;         for (int ai = 0; ai < 2; ++ai)
; #pragma unroll
;             for (int m = 0; m < 4; ++m) { const int rl = rl0 + ai * HALF + m * 16; bf16_t* rowp = O + (size_t)(u.pm * BM + rl) * ldc + col0;
;                 const float s = rst[u.idx * BM + rl];
; #pragma unroll
;                 for (int bj = 0; bj < 2; ++bj) { f32x4 v0 = acc[ai][bj][m][0] * s, v1 = acc[ai][bj][m][1] * s;
;                     if (ACT == 1) {
; #pragma unroll
;                         for (int e = 0; e < 4; ++e) { const float a = fmaxf(v0[e], 0.f), b = fmaxf(v1[e], 0.f); v0[e] = a * a; v1[e] = b * b; } }
;                     u32x4 w; w.x = cvt_pk_bf16(v0[0], v0[1]); w.y = cvt_pk_bf16(v0[2], v0[3]); w.z = cvt_pk_bf16(v1[0], v1[1]); w.w = cvt_pk_bf16(v1[2], v1[3]);
;                     __builtin_nontemporal_store(w, (u32x4*)(rowp + bj * HALF)); } }
;     }
	global_store_dwordx4 v[178:179], v[160:163], off offset:256 nt
	v_max_f32_e32 v102, 0, v102
	v_max_f32_e32 v101, 0, v101
	v_mul_f32_e32 v106, v98, v98
	v_max_f32_e32 v98, 0, v103
	v_mul_f32_e32 v103, v99, v99
	v_max_f32_e32 v99, 0, v104
	v_mul_f32_e32 v104, v100, v100
	v_max_f32_e32 v100, 0, v105
	v_mul_f32_e32 v98, v98, v98
	v_mul_f32_e32 v99, v99, v99
	v_mul_f32_e32 v100, v100, v100
	v_mul_f32_e32 v102, v102, v102
	v_mul_f32_e32 v101, v101, v101
	v_cvt_pk_bf16_f32 v98, v102, v98
	v_cvt_pk_bf16_f32 v99, v99, v100
	v_cvt_pk_bf16_f32 v100, v106, v103
	v_cvt_pk_bf16_f32 v101, v104, v101
	ds_bpermute_b32 v160, v246, v98
	ds_bpermute_b32 v161, v246, v99
	ds_bpermute_b32 v162, v246, v100
	ds_bpermute_b32 v163, v246, v101
	v_lshl_add_u64 v[178:179], v[114:115], 0, v[180:181]
	s_waitcnt lgkmcnt(4)
	global_store_dwordx4 v[164:165], v[156:159], off nt
	s_waitcnt lgkmcnt(4)
	v_mov_b32_e32 v100, v197
	v_pk_mul_f32 v[90:91], v[90:91], v[100:101] op_sel_hi:[1,0]
	v_add_u32_e32 v98, 32, v140
	v_ashrrev_i32_e32 v99, 31, v98
	v_pk_mul_f32 v[94:95], v[94:95], v[100:101] op_sel_hi:[1,0]
	v_pk_mul_f32 v[92:93], v[92:93], v[100:101] op_sel_hi:[1,0]
	v_max_f32_e32 v90, 0, v90
	v_lshlrev_b64 v[98:99], 13, v[98:99]
	v_pk_mul_f32 v[96:97], v[96:97], v[100:101] op_sel_hi:[1,0]
	v_mul_f32_e32 v101, v90, v90
	v_max_f32_e32 v90, 0, v95
	v_max_f32_e32 v91, 0, v91
	v_max_f32_e32 v92, 0, v92
	v_lshl_add_u64 v[98:99], s[28:29], 0, v[98:99]
	v_max_f32_e32 v94, 0, v94
	v_mul_f32_e32 v90, v90, v90
	v_mul_f32_e32 v95, v91, v91
	v_max_f32_e32 v91, 0, v96
	v_mul_f32_e32 v96, v92, v92
	v_max_f32_e32 v92, 0, v97
	v_max_f32_e32 v93, 0, v93
	v_pk_mul_f32 v[84:85], v[84:85], v[100:101] op_sel_hi:[1,0]
	v_pk_mul_f32 v[82:83], v[82:83], v[100:101] op_sel_hi:[1,0]
	v_lshl_add_u64 v[98:99], v[98:99], 0, v[142:143]
	v_mul_f32_e32 v94, v94, v94
	v_mul_f32_e32 v91, v91, v91
	v_mul_f32_e32 v92, v92, v92
	v_mul_f32_e32 v93, v93, v93
	v_cvt_pk_bf16_f32 v90, v94, v90
	v_pk_mul_f32 v[88:89], v[88:89], v[100:101] op_sel_hi:[1,0]
	v_pk_mul_f32 v[86:87], v[86:87], v[100:101] op_sel_hi:[1,0]
	v_max_f32_e32 v82, 0, v82
	v_max_f32_e32 v83, 0, v83
	v_max_f32_e32 v84, 0, v84
	v_cvt_pk_bf16_f32 v91, v91, v92
	v_cvt_pk_bf16_f32 v92, v101, v95
	v_cvt_pk_bf16_f32 v93, v96, v93
	ds_bpermute_b32 v156, v246, v90
	ds_bpermute_b32 v157, v246, v91
	ds_bpermute_b32 v158, v246, v92
	ds_bpermute_b32 v159, v246, v93
	v_lshl_add_u64 v[164:165], v[98:99], 0, v[180:181]
	s_waitcnt lgkmcnt(4)
	global_store_dwordx4 v[178:179], v[160:163], off offset:256 nt
	v_max_f32_e32 v86, 0, v86
	v_max_f32_e32 v85, 0, v85
	v_mul_f32_e32 v90, v82, v82
	v_max_f32_e32 v82, 0, v87
	v_mul_f32_e32 v87, v83, v83
	v_max_f32_e32 v83, 0, v88
	v_mul_f32_e32 v88, v84, v84
	v_max_f32_e32 v84, 0, v89
	v_mul_f32_e32 v82, v82, v82
	v_mul_f32_e32 v83, v83, v83
	v_mul_f32_e32 v84, v84, v84
	v_mul_f32_e32 v86, v86, v86
	v_mul_f32_e32 v85, v85, v85
	v_cvt_pk_bf16_f32 v82, v86, v82
	v_cvt_pk_bf16_f32 v83, v83, v84
	v_cvt_pk_bf16_f32 v84, v90, v87
	v_cvt_pk_bf16_f32 v85, v88, v85
	ds_bpermute_b32 v160, v246, v82
	ds_bpermute_b32 v161, v246, v83
	ds_bpermute_b32 v162, v246, v84
	ds_bpermute_b32 v163, v246, v85
	v_lshl_add_u64 v[178:179], v[98:99], 0, v[180:181]
	s_waitcnt lgkmcnt(4)
	global_store_dwordx4 v[164:165], v[156:159], off nt
	s_waitcnt lgkmcnt(4)
	v_mov_b32_e32 v84, v198
	v_pk_mul_f32 v[74:75], v[74:75], v[84:85] op_sel_hi:[1,0]
	v_add_u32_e32 v82, 48, v140
	v_ashrrev_i32_e32 v83, 31, v82
	v_pk_mul_f32 v[78:79], v[78:79], v[84:85] op_sel_hi:[1,0]
	v_pk_mul_f32 v[76:77], v[76:77], v[84:85] op_sel_hi:[1,0]
	v_max_f32_e32 v74, 0, v74
	v_lshlrev_b64 v[82:83], 13, v[82:83]
	v_pk_mul_f32 v[80:81], v[80:81], v[84:85] op_sel_hi:[1,0]
	v_mul_f32_e32 v85, v74, v74
	v_max_f32_e32 v74, 0, v79
	v_max_f32_e32 v75, 0, v75
	v_max_f32_e32 v76, 0, v76
	v_lshl_add_u64 v[82:83], s[28:29], 0, v[82:83]
	v_max_f32_e32 v78, 0, v78
	v_mul_f32_e32 v74, v74, v74
	v_mul_f32_e32 v79, v75, v75
	v_max_f32_e32 v75, 0, v80
	v_mul_f32_e32 v80, v76, v76
	v_max_f32_e32 v76, 0, v81
	v_max_f32_e32 v77, 0, v77
	v_pk_mul_f32 v[68:69], v[68:69], v[84:85] op_sel_hi:[1,0]
	v_pk_mul_f32 v[66:67], v[66:67], v[84:85] op_sel_hi:[1,0]
	v_lshl_add_u64 v[82:83], v[82:83], 0, v[142:143]
	v_mul_f32_e32 v78, v78, v78
	v_mul_f32_e32 v75, v75, v75
	v_mul_f32_e32 v76, v76, v76
	v_mul_f32_e32 v77, v77, v77
	v_cvt_pk_bf16_f32 v74, v78, v74
	v_pk_mul_f32 v[72:73], v[72:73], v[84:85] op_sel_hi:[1,0]
	v_pk_mul_f32 v[70:71], v[70:71], v[84:85] op_sel_hi:[1,0]
	v_max_f32_e32 v66, 0, v66
	v_max_f32_e32 v67, 0, v67
	v_max_f32_e32 v68, 0, v68
	v_cvt_pk_bf16_f32 v75, v75, v76
	v_cvt_pk_bf16_f32 v76, v85, v79
	v_cvt_pk_bf16_f32 v77, v80, v77
	ds_bpermute_b32 v156, v246, v74
	ds_bpermute_b32 v157, v246, v75
	ds_bpermute_b32 v158, v246, v76
	ds_bpermute_b32 v159, v246, v77
	v_lshl_add_u64 v[164:165], v[82:83], 0, v[180:181]
	s_waitcnt lgkmcnt(4)
	global_store_dwordx4 v[178:179], v[160:163], off offset:256 nt
	v_max_f32_e32 v70, 0, v70
	v_max_f32_e32 v69, 0, v69
	v_mul_f32_e32 v74, v66, v66
	v_max_f32_e32 v66, 0, v71
	v_mul_f32_e32 v71, v67, v67
	v_max_f32_e32 v67, 0, v72
	v_mul_f32_e32 v72, v68, v68
	v_max_f32_e32 v68, 0, v73
	v_mul_f32_e32 v66, v66, v66
	v_mul_f32_e32 v67, v67, v67
	v_mul_f32_e32 v68, v68, v68
	v_mul_f32_e32 v70, v70, v70
	v_mul_f32_e32 v69, v69, v69
	v_cvt_pk_bf16_f32 v66, v70, v66
	v_cvt_pk_bf16_f32 v67, v67, v68
	v_cvt_pk_bf16_f32 v68, v74, v71
	v_cvt_pk_bf16_f32 v69, v72, v69
	ds_bpermute_b32 v160, v246, v66
	ds_bpermute_b32 v161, v246, v67
	ds_bpermute_b32 v162, v246, v68
	ds_bpermute_b32 v163, v246, v69
	v_lshl_add_u64 v[178:179], v[82:83], 0, v[180:181]
	s_waitcnt lgkmcnt(4)
; __device__ __forceinline__ unsigned cvt_pk_bf16(float lo, float hi) { unsigned r; asm volatile("v_cvt_pk_bf16_f32 %0, %1, %2" : "=v"(r) : "v"(lo), "v"(hi)); return r; }
;     __device__ __forceinline__ void operator()(const f32x4 (&acc)[2][2][4][2], const Unit& u, int wr, int wc, int fr, int fq) const {
;         asm volatile("" : "+v"(fr), "+v"(fq));
;         const int rl0 = wr * 64 + fr, col0 = u.pn * BM + wc * 32 + 8 * fq;
; #pragma unroll
;         for (int ai = 0; ai < 2; ++ai)
; #pragma unroll
;             for (int m = 0; m < 4; ++m) { const int rl = rl0 + ai * HALF + m * 16; bf16_t* rowp = O + (size_t)(u.pm * BM + rl) * ldc + col0;
;                 const float s = rst[u.idx * BM + rl];
; #pragma unroll
;                 for (int bj = 0; bj < 2; ++bj) { f32x4 v0 = acc[ai][bj][m][0] * s, v1 = acc[ai][bj][m][1] * s;
;                     if (ACT == 1) {
; #pragma unroll
;                         for (int e = 0; e < 4; ++e) { const float a = fmaxf(v0[e], 0.f), b = fmaxf(v1[e], 0.f); v0[e] = a * a; v1[e] = b * b; } }
;                     u32x4 w; w.x = cvt_pk_bf16(v0[0], v0[1]); w.y = cvt_pk_bf16(v0[2], v0[3]); w.z = cvt_pk_bf16(v1[0], v1[1]); w.w = cvt_pk_bf16(v1[2], v1[3]);
;                     __builtin_nontemporal_store(w, (u32x4*)(rowp + bj * HALF)); } }
;     }
	global_store_dwordx4 v[164:165], v[156:159], off nt
	s_waitcnt lgkmcnt(4)
	v_mov_b32_e32 v68, v199
	v_pk_mul_f32 v[58:59], v[58:59], v[68:69] op_sel_hi:[1,0]
	v_add_u32_e32 v66, 0x80, v140
	v_ashrrev_i32_e32 v67, 31, v66
	v_pk_mul_f32 v[62:63], v[62:63], v[68:69] op_sel_hi:[1,0]
	v_pk_mul_f32 v[60:61], v[60:61], v[68:69] op_sel_hi:[1,0]
	v_max_f32_e32 v58, 0, v58
	v_lshlrev_b64 v[66:67], 13, v[66:67]
	v_pk_mul_f32 v[64:65], v[64:65], v[68:69] op_sel_hi:[1,0]
	v_mul_f32_e32 v69, v58, v58
	v_max_f32_e32 v58, 0, v63
	v_max_f32_e32 v59, 0, v59
	v_max_f32_e32 v60, 0, v60
	v_lshl_add_u64 v[66:67], s[28:29], 0, v[66:67]
	v_max_f32_e32 v62, 0, v62
	v_mul_f32_e32 v58, v58, v58
	v_mul_f32_e32 v63, v59, v59
	v_max_f32_e32 v59, 0, v64
	v_mul_f32_e32 v64, v60, v60
	v_max_f32_e32 v60, 0, v65
	v_max_f32_e32 v61, 0, v61
	v_pk_mul_f32 v[52:53], v[52:53], v[68:69] op_sel_hi:[1,0]
	v_pk_mul_f32 v[50:51], v[50:51], v[68:69] op_sel_hi:[1,0]
	v_lshl_add_u64 v[66:67], v[66:67], 0, v[142:143]
	v_mul_f32_e32 v62, v62, v62
	v_mul_f32_e32 v59, v59, v59
	v_mul_f32_e32 v60, v60, v60
	v_mul_f32_e32 v61, v61, v61
	v_cvt_pk_bf16_f32 v58, v62, v58
	v_pk_mul_f32 v[56:57], v[56:57], v[68:69] op_sel_hi:[1,0]
	v_pk_mul_f32 v[54:55], v[54:55], v[68:69] op_sel_hi:[1,0]
	v_max_f32_e32 v50, 0, v50
	v_max_f32_e32 v51, 0, v51
	v_max_f32_e32 v52, 0, v52
	v_cvt_pk_bf16_f32 v59, v59, v60
	v_cvt_pk_bf16_f32 v60, v69, v63
	v_cvt_pk_bf16_f32 v61, v64, v61
	ds_bpermute_b32 v156, v246, v58
	ds_bpermute_b32 v157, v246, v59
	ds_bpermute_b32 v158, v246, v60
	ds_bpermute_b32 v159, v246, v61
	v_lshl_add_u64 v[164:165], v[66:67], 0, v[180:181]
	s_waitcnt lgkmcnt(4)
	global_store_dwordx4 v[178:179], v[160:163], off offset:256 nt
	v_max_f32_e32 v54, 0, v54
	v_max_f32_e32 v53, 0, v53
	v_mul_f32_e32 v58, v50, v50
	v_max_f32_e32 v50, 0, v55
	v_mul_f32_e32 v55, v51, v51
	v_max_f32_e32 v51, 0, v56
	v_mul_f32_e32 v56, v52, v52
	v_max_f32_e32 v52, 0, v57
	v_mul_f32_e32 v50, v50, v50
	v_mul_f32_e32 v51, v51, v51
	v_mul_f32_e32 v52, v52, v52
	v_mul_f32_e32 v54, v54, v54
	v_mul_f32_e32 v53, v53, v53
	v_cvt_pk_bf16_f32 v50, v54, v50
	v_cvt_pk_bf16_f32 v51, v51, v52
	v_cvt_pk_bf16_f32 v52, v58, v55
	v_cvt_pk_bf16_f32 v53, v56, v53
	ds_bpermute_b32 v160, v246, v50
	ds_bpermute_b32 v161, v246, v51
	ds_bpermute_b32 v162, v246, v52
	ds_bpermute_b32 v163, v246, v53
	v_lshl_add_u64 v[178:179], v[66:67], 0, v[180:181]
	s_waitcnt lgkmcnt(4)
	global_store_dwordx4 v[164:165], v[156:159], off nt
	s_waitcnt lgkmcnt(4)
	v_mov_b32_e32 v52, v200
	v_pk_mul_f32 v[42:43], v[42:43], v[52:53] op_sel_hi:[1,0]
	v_add_u32_e32 v50, 0x90, v140
	v_ashrrev_i32_e32 v51, 31, v50
	v_pk_mul_f32 v[46:47], v[46:47], v[52:53] op_sel_hi:[1,0]
	v_pk_mul_f32 v[44:45], v[44:45], v[52:53] op_sel_hi:[1,0]
	v_max_f32_e32 v42, 0, v42
	v_lshlrev_b64 v[50:51], 13, v[50:51]
	v_pk_mul_f32 v[48:49], v[48:49], v[52:53] op_sel_hi:[1,0]
	v_mul_f32_e32 v53, v42, v42
	v_max_f32_e32 v42, 0, v47
	v_max_f32_e32 v43, 0, v43
	v_max_f32_e32 v44, 0, v44
	v_lshl_add_u64 v[50:51], s[28:29], 0, v[50:51]
	v_max_f32_e32 v46, 0, v46
	v_mul_f32_e32 v42, v42, v42
	v_mul_f32_e32 v47, v43, v43
	v_max_f32_e32 v43, 0, v48
	v_mul_f32_e32 v48, v44, v44
	v_max_f32_e32 v44, 0, v49
	v_max_f32_e32 v45, 0, v45
	v_pk_mul_f32 v[36:37], v[36:37], v[52:53] op_sel_hi:[1,0]
	v_pk_mul_f32 v[34:35], v[34:35], v[52:53] op_sel_hi:[1,0]
	v_lshl_add_u64 v[50:51], v[50:51], 0, v[142:143]
	v_mul_f32_e32 v46, v46, v46
	v_mul_f32_e32 v43, v43, v43
	v_mul_f32_e32 v44, v44, v44
	v_mul_f32_e32 v45, v45, v45
	v_cvt_pk_bf16_f32 v42, v46, v42
	v_pk_mul_f32 v[40:41], v[40:41], v[52:53] op_sel_hi:[1,0]
	v_pk_mul_f32 v[38:39], v[38:39], v[52:53] op_sel_hi:[1,0]
	v_max_f32_e32 v34, 0, v34
	v_max_f32_e32 v35, 0, v35
	v_max_f32_e32 v36, 0, v36
	v_cvt_pk_bf16_f32 v43, v43, v44
	v_cvt_pk_bf16_f32 v44, v53, v47
	v_cvt_pk_bf16_f32 v45, v48, v45
	ds_bpermute_b32 v156, v246, v42
	ds_bpermute_b32 v157, v246, v43
	ds_bpermute_b32 v158, v246, v44
	ds_bpermute_b32 v159, v246, v45
	v_lshl_add_u64 v[164:165], v[50:51], 0, v[180:181]
	s_waitcnt lgkmcnt(4)
	global_store_dwordx4 v[178:179], v[160:163], off offset:256 nt
	v_max_f32_e32 v38, 0, v38
	v_max_f32_e32 v37, 0, v37
	v_mul_f32_e32 v42, v34, v34
	v_max_f32_e32 v34, 0, v39
	v_mul_f32_e32 v39, v35, v35
	v_max_f32_e32 v35, 0, v40
	v_mul_f32_e32 v40, v36, v36
	v_max_f32_e32 v36, 0, v41
	v_mul_f32_e32 v34, v34, v34
	v_mul_f32_e32 v35, v35, v35
	v_mul_f32_e32 v36, v36, v36
	v_mul_f32_e32 v38, v38, v38
	v_mul_f32_e32 v37, v37, v37
	v_cvt_pk_bf16_f32 v34, v38, v34
	v_cvt_pk_bf16_f32 v35, v35, v36
	v_cvt_pk_bf16_f32 v36, v42, v39
	v_cvt_pk_bf16_f32 v37, v40, v37
	ds_bpermute_b32 v160, v246, v34
	ds_bpermute_b32 v161, v246, v35
	ds_bpermute_b32 v162, v246, v36
	ds_bpermute_b32 v163, v246, v37
	v_lshl_add_u64 v[178:179], v[50:51], 0, v[180:181]
	s_waitcnt lgkmcnt(4)
	global_store_dwordx4 v[164:165], v[156:159], off nt
	s_waitcnt lgkmcnt(4)
; __device__ __forceinline__ unsigned cvt_pk_bf16(float lo, float hi) { unsigned r; asm volatile("v_cvt_pk_bf16_f32 %0, %1, %2" : "=v"(r) : "v"(lo), "v"(hi)); return r; }
;     __device__ __forceinline__ void operator()(const f32x4 (&acc)[2][2][4][2], const Unit& u, int wr, int wc, int fr, int fq) const {
;         asm volatile("" : "+v"(fr), "+v"(fq));
;         const int rl0 = wr * 64 + fr, col0 = u.pn * BM + wc * 32 + 8 * fq;
; #pragma unroll
;         for (int ai = 0; ai < 2; ++ai)
; #pragma unroll
;             for (int m = 0; m < 4; ++m) { const int rl = rl0 + ai * HALF + m * 16; bf16_t* rowp = O + (size_t)(u.pm * BM + rl) * ldc + col0;
;                 const float s = rst[u.idx * BM + rl];
; #pragma unroll
;                 for (int bj = 0; bj < 2; ++bj) { f32x4 v0 = acc[ai][bj][m][0] * s, v1 = acc[ai][bj][m][1] * s;
;                     if (ACT == 1) {
; #pragma unroll
;                         for (int e = 0; e < 4; ++e) { const float a = fmaxf(v0[e], 0.f), b = fmaxf(v1[e], 0.f); v0[e] = a * a; v1[e] = b * b; } }
;                     u32x4 w; w.x = cvt_pk_bf16(v0[0], v0[1]); w.y = cvt_pk_bf16(v0[2], v0[3]); w.z = cvt_pk_bf16(v1[0], v1[1]); w.w = cvt_pk_bf16(v1[2], v1[3]);
;                     __builtin_nontemporal_store(w, (u32x4*)(rowp + bj * HALF)); } }
;     }
	v_mov_b32_e32 v36, v201
	v_pk_mul_f32 v[26:27], v[26:27], v[36:37] op_sel_hi:[1,0]
	v_add_u32_e32 v34, 0xa0, v140
	v_ashrrev_i32_e32 v35, 31, v34
	v_pk_mul_f32 v[30:31], v[30:31], v[36:37] op_sel_hi:[1,0]
	v_pk_mul_f32 v[28:29], v[28:29], v[36:37] op_sel_hi:[1,0]
	v_max_f32_e32 v26, 0, v26
	v_lshlrev_b64 v[34:35], 13, v[34:35]
	v_pk_mul_f32 v[32:33], v[32:33], v[36:37] op_sel_hi:[1,0]
	v_mul_f32_e32 v37, v26, v26
	v_max_f32_e32 v26, 0, v31
	v_max_f32_e32 v27, 0, v27
	v_max_f32_e32 v28, 0, v28
	v_lshl_add_u64 v[34:35], s[28:29], 0, v[34:35]
	v_max_f32_e32 v30, 0, v30
	v_mul_f32_e32 v26, v26, v26
	v_mul_f32_e32 v31, v27, v27
	v_max_f32_e32 v27, 0, v32
	v_mul_f32_e32 v32, v28, v28
	v_max_f32_e32 v28, 0, v33
	v_max_f32_e32 v29, 0, v29
	v_pk_mul_f32 v[20:21], v[20:21], v[36:37] op_sel_hi:[1,0]
	v_pk_mul_f32 v[18:19], v[18:19], v[36:37] op_sel_hi:[1,0]
	v_lshl_add_u64 v[34:35], v[34:35], 0, v[142:143]
	v_mul_f32_e32 v30, v30, v30
	v_mul_f32_e32 v27, v27, v27
	v_mul_f32_e32 v28, v28, v28
	v_mul_f32_e32 v29, v29, v29
	v_cvt_pk_bf16_f32 v26, v30, v26
	v_pk_mul_f32 v[24:25], v[24:25], v[36:37] op_sel_hi:[1,0]
	v_pk_mul_f32 v[22:23], v[22:23], v[36:37] op_sel_hi:[1,0]
	v_max_f32_e32 v18, 0, v18
	v_max_f32_e32 v19, 0, v19
	v_max_f32_e32 v20, 0, v20
	v_cvt_pk_bf16_f32 v27, v27, v28
	v_cvt_pk_bf16_f32 v28, v37, v31
	v_cvt_pk_bf16_f32 v29, v32, v29
	ds_bpermute_b32 v156, v246, v26
	ds_bpermute_b32 v157, v246, v27
	ds_bpermute_b32 v158, v246, v28
	ds_bpermute_b32 v159, v246, v29
	v_lshl_add_u64 v[164:165], v[34:35], 0, v[180:181]
	s_waitcnt lgkmcnt(4)
	global_store_dwordx4 v[178:179], v[160:163], off offset:256 nt
	v_max_f32_e32 v22, 0, v22
	v_max_f32_e32 v21, 0, v21
	v_mul_f32_e32 v26, v18, v18
	v_max_f32_e32 v18, 0, v23
	v_mul_f32_e32 v23, v19, v19
	v_max_f32_e32 v19, 0, v24
	v_mul_f32_e32 v24, v20, v20
	v_max_f32_e32 v20, 0, v25
	v_mul_f32_e32 v18, v18, v18
	v_mul_f32_e32 v19, v19, v19
	v_mul_f32_e32 v20, v20, v20
	v_mul_f32_e32 v22, v22, v22
	v_mul_f32_e32 v21, v21, v21
	v_cvt_pk_bf16_f32 v18, v22, v18
	v_cvt_pk_bf16_f32 v19, v19, v20
	v_cvt_pk_bf16_f32 v20, v26, v23
	v_cvt_pk_bf16_f32 v21, v24, v21
	ds_bpermute_b32 v160, v246, v18
	ds_bpermute_b32 v161, v246, v19
	ds_bpermute_b32 v162, v246, v20
	ds_bpermute_b32 v163, v246, v21
	v_lshl_add_u64 v[178:179], v[34:35], 0, v[180:181]
	s_waitcnt lgkmcnt(4)
	global_store_dwordx4 v[164:165], v[156:159], off nt
	s_waitcnt lgkmcnt(4)
	v_mov_b32_e32 v20, v202
	v_pk_mul_f32 v[10:11], v[10:11], v[20:21] op_sel_hi:[1,0]
	v_add_u32_e32 v18, 0xb0, v140
	v_ashrrev_i32_e32 v19, 31, v18
	v_pk_mul_f32 v[14:15], v[14:15], v[20:21] op_sel_hi:[1,0]
	v_pk_mul_f32 v[12:13], v[12:13], v[20:21] op_sel_hi:[1,0]
	v_max_f32_e32 v10, 0, v10
	v_lshlrev_b64 v[18:19], 13, v[18:19]
	v_pk_mul_f32 v[16:17], v[16:17], v[20:21] op_sel_hi:[1,0]
	v_mul_f32_e32 v21, v10, v10
	v_max_f32_e32 v10, 0, v15
	v_max_f32_e32 v11, 0, v11
	v_max_f32_e32 v12, 0, v12
	v_lshl_add_u64 v[18:19], s[28:29], 0, v[18:19]
	v_max_f32_e32 v14, 0, v14
	v_mul_f32_e32 v10, v10, v10
	v_mul_f32_e32 v15, v11, v11
	v_max_f32_e32 v11, 0, v16
	v_mul_f32_e32 v16, v12, v12
	v_max_f32_e32 v12, 0, v17
	v_max_f32_e32 v13, 0, v13
	v_pk_mul_f32 v[4:5], v[4:5], v[20:21] op_sel_hi:[1,0]
	v_pk_mul_f32 v[2:3], v[2:3], v[20:21] op_sel_hi:[1,0]
	v_lshl_add_u64 v[18:19], v[18:19], 0, v[142:143]
	v_mul_f32_e32 v14, v14, v14
	v_mul_f32_e32 v11, v11, v11
	v_mul_f32_e32 v12, v12, v12
	v_mul_f32_e32 v13, v13, v13
	v_cvt_pk_bf16_f32 v10, v14, v10
	v_pk_mul_f32 v[8:9], v[8:9], v[20:21] op_sel_hi:[1,0]
	v_pk_mul_f32 v[6:7], v[6:7], v[20:21] op_sel_hi:[1,0]
	v_max_f32_e32 v2, 0, v2
	v_max_f32_e32 v3, 0, v3
	v_max_f32_e32 v4, 0, v4
	v_cvt_pk_bf16_f32 v11, v11, v12
	v_cvt_pk_bf16_f32 v12, v21, v15
	v_cvt_pk_bf16_f32 v13, v16, v13
	ds_bpermute_b32 v156, v246, v10
	ds_bpermute_b32 v157, v246, v11
	ds_bpermute_b32 v158, v246, v12
	ds_bpermute_b32 v159, v246, v13
	v_lshl_add_u64 v[164:165], v[18:19], 0, v[180:181]
	s_waitcnt lgkmcnt(4)
	global_store_dwordx4 v[178:179], v[160:163], off offset:256 nt
	v_max_f32_e32 v5, 0, v5
	v_max_f32_e32 v6, 0, v6
	v_mul_f32_e32 v10, v2, v2
	v_max_f32_e32 v2, 0, v7
	v_mul_f32_e32 v7, v3, v3
	v_max_f32_e32 v3, 0, v8
	v_mul_f32_e32 v8, v4, v4
	v_max_f32_e32 v4, 0, v9
	v_mul_f32_e32 v2, v2, v2
	v_mul_f32_e32 v3, v3, v3
	v_mul_f32_e32 v4, v4, v4
	v_mul_f32_e32 v5, v5, v5
	v_mul_f32_e32 v6, v6, v6
	v_cvt_pk_bf16_f32 v2, v6, v2
	v_cvt_pk_bf16_f32 v3, v3, v4
	v_cvt_pk_bf16_f32 v4, v10, v7
	v_cvt_pk_bf16_f32 v5, v8, v5
	ds_bpermute_b32 v160, v246, v2
	ds_bpermute_b32 v161, v246, v3
	ds_bpermute_b32 v162, v246, v4
	ds_bpermute_b32 v163, v246, v5
	v_lshl_add_u64 v[178:179], v[18:19], 0, v[180:181]
	s_waitcnt lgkmcnt(4)
	global_store_dwordx4 v[164:165], v[156:159], off nt
	s_waitcnt lgkmcnt(0)
	global_store_dwordx4 v[178:179], v[160:163], off offset:256 nt
	s_cbranch_vccnz .LBB0_484
	s_andn2_b64 vcc, exec, s[22:23]
	s_cbranch_vccnz .LBB0_483
	s_barrier
	s_branch .LBB0_483
